# fox loop: packed fp32 FMAs feeding the QK MFMA accumulators split into scalar FMAs (same values)
# speedup vs baseline: 1.0124x; 1.0065x over previous
; #define LAS __attribute__((address_space(3)))
; #define MFMA32(a, b, c) __builtin_amdgcn_mfma_f32_32x32x16_bf16((a), (b), (c), 0, 0, 0)
; #define ATT_SB() __builtin_amdgcn_sched_barrier(0)
; template <bool FOX> ...
;     ...
;                 LAS const float* ck = (LAS const float*)(lds + ATT_CK + buf * 512) + 64 * stream;
;                 ckfirst = ck[0] * LOG2E;
;                 ck += 8 * hi;
;                 const float cqm = cq2 - mref;
; #pragma unroll
;                 for (int rr = 0; rr < 2; ++rr) {
;                     const f32x4 a0 = *(LAS const f32x4*)(ck + 16 * rr), a1 = *(LAS const f32x4*)(ck + 16 * rr + 4), b0 = *(LAS const f32x4*)(ck + 32 + 16 * rr), b1 = *(LAS const f32x4*)(ck + 32 + 16 * rr + 4);
; #pragma unroll
;                     for (int e = 0; e < 4; ++e) { s0[8 * rr + e] = cqm - LOG2E * a0[e]; s0[8 * rr + 4 + e] = cqm - LOG2E * a1[e]; s1[8 * rr + e] = cqm - LOG2E * b0[e]; s1[8 * rr + 4 + e] = cqm - LOG2E * b1[e]; }
;                 }
;                 ATT_SB();
;                 s0 = MFMA32(kf[0], qf[0], s0); s1 = MFMA32(kf[1], qf[0], s1);
;             } else {
;                 ATT_SB();
;                 s0 = MFMA32(kf[0], qf[0], negm); s1 = MFMA32(kf[1], qf[0], negm);
;             }
; #pragma unroll
;             for (int s = 1; s < 4; ++s) { s0 = MFMA32(kf[2 * s], qf[s], s0); s1 = MFMA32(kf[2 * s + 1], qf[s], s1); }
.LBB0_507:
	s_lshl_b32 s3, s18, 9
	s_add_i32 s3, s22, s3
	v_mov_b32_e32 v1, s3
	v_lshl_add_u32 v15, v148, 2, s3
	ds_read_b32 v1, v1
	ds_read_b128 v[50:53], v15
	ds_read_b128 v[164:167], v15 offset:128
	ds_read_b128 v[54:57], v15 offset:80
	ds_read_b128 v[58:61], v15 offset:16
	ds_read_b128 v[62:65], v15 offset:64
	ds_read_b128 v[168:171], v15 offset:144
	ds_read_b128 v[172:175], v15 offset:192
	ds_read_b128 v[176:179], v15 offset:208
	v_sub_f32_e32 v14, v154, v161
	s_waitcnt lgkmcnt(0)
	v_fma_f32 v66, -v50, s26, v14
	v_fma_f32 v67, -v51, s26, v14
	v_fma_f32 v80, -v56, s26, v14
	v_fma_f32 v81, -v57, s26, v14
	v_fma_f32 v76, -v64, s26, v14
	v_fma_f32 v77, -v65, s26, v14
	v_fma_f32 v72, -v60, s26, v14
	v_fma_f32 v73, -v61, s26, v14
	v_fma_f32 v68, -v52, s26, v14
	v_fma_f32 v69, -v53, s26, v14
	v_fma_f32 v64, -v178, s26, v14
	v_fma_f32 v65, -v179, s26, v14
	v_fma_f32 v60, -v174, s26, v14
	v_fma_f32 v61, -v175, s26, v14
	v_fma_f32 v56, -v170, s26, v14
	v_fma_f32 v57, -v171, s26, v14
	v_fma_f32 v78, -v54, s26, v14
	v_fma_f32 v79, -v55, s26, v14
	v_fma_f32 v74, -v62, s26, v14
	v_fma_f32 v75, -v63, s26, v14
	v_fma_f32 v70, -v58, s26, v14
	v_fma_f32 v71, -v59, s26, v14
	v_fma_f32 v62, -v176, s26, v14
	v_fma_f32 v63, -v177, s26, v14
	v_fma_f32 v58, -v172, s26, v14
	v_fma_f32 v59, -v173, s26, v14
	v_fma_f32 v54, -v168, s26, v14
	v_fma_f32 v55, -v169, s26, v14
	v_fma_f32 v50, -v164, s26, v14
	v_fma_f32 v51, -v165, s26, v14
	v_fma_f32 v52, -v166, s26, v14
	v_fma_f32 v53, -v167, s26, v14
	v_mfma_f32_32x32x16_bf16 v[66:81], v[130:133], v[82:85], v[66:81]
	s_nop 0
	v_mfma_f32_32x32x16_bf16 v[50:65], v[122:125], v[82:85], v[50:65]
	v_mul_f32_e32 v122, 0x3fb8aa3b, v1
	v_mfma_f32_32x32x16_bf16 v[66:81], v[126:129], v[86:89], v[66:81]
	v_mfma_f32_32x32x16_bf16 v[50:65], v[114:117], v[86:89], v[50:65]
	v_mfma_f32_32x32x16_bf16 v[66:81], v[118:121], v[90:93], v[66:81]
	v_mfma_f32_32x32x16_bf16 v[50:65], v[6:9], v[90:93], v[50:65]
	v_mfma_f32_32x32x16_bf16 v[66:81], v[10:13], v[94:97], v[66:81]
	v_mfma_f32_32x32x16_bf16 v[50:65], v[2:5], v[94:97], v[50:65]
	s_branch .LBB0_509
